# gather_u: first dot of each accumulator uses v_dot8_i32_i4 with zero addend instead of zeroing the accumulators (2 fewer VALU per row group)
# baseline (speedup 1.0000x reference)
; __device__ void phase_gather_u(const Params& p) {
;     ...
; #pragma unroll
;         for (int k = 0; k < 16; ++k) {
;           int j = jfirst, e = efirst;
;           if (m0) { const int jj = __builtin_amdgcn_readfirstlane(__ffsll((long long)m0) - 1); m0 &= m0 - 1ull; j = jj; e = __builtin_amdgcn_readlane(idA, jj); }
;           else if (m1) { const int jj = __builtin_amdgcn_readfirstlane(__ffsll((long long)m1) - 1); m1 &= m1 - 1ull; j = 64 + jj; e = __builtin_amdgcn_readlane(idB, jj); }
;           jk[k] = j;
;           rw[k] = *(const u32x4*)(ub + (size_t)e * 1024 + lane * 16);
;         }
; #pragma unroll
;         for (int bt = 0; bt < 2; ++bt) {
;           int dv[8];
; #pragma unroll
;           for (int k = 0; k < 8; ++k) {
;             int dh = 0, dl = 0;
; #pragma unroll
;             for (int q = 0; q < 4; ++q) {
;               dh = __builtin_amdgcn_sdot8((int)rw[bt * 8 + k][q], (int)ph[q], dh, false);
;               dl = __builtin_amdgcn_sdot8((int)rw[bt * 8 + k][q], (int)pl[q], dl, false);
;             }
;             dv[k] = 16 * dh + dl;
;           }
;           int a4[4], a2[2];
; #pragma unroll
;           for (int k = 0; k < 4; ++k) {
;             const int mine = b5 ? dv[k + 4] : dv[k], oth = b5 ? dv[k] : dv[k + 4];
;             a4[k] = mine + __shfl_xor(oth, 32);
;           }
; #pragma unroll
;           for (int k = 0; k < 2; ++k) {
;             const int mine = b4 ? a4[k + 2] : a4[k], oth = b4 ? a4[k] : a4[k + 2];
;             a2[k] = mine + __shfl_xor(oth, 16);
;           }
;           int c1;
;           {
;             const int mine = b3 ? a2[1] : a2[0], oth = b3 ? a2[0] : a2[1];
;             c1 = mine + __shfl_xor(oth, 8);
;           }
;           c1 += __shfl_xor(c1, 4);
;           c1 += __shfl_xor(c1, 2);
;           c1 += __shfl_xor(c1, 1);
;           const int val = __shfl(c1, srcl);
;           int jsel = jk[bt * 8];
; #pragma unroll
;           for (int k = 1; k < 8; ++k) jsel = (lane == k) ? jk[bt * 8 + k] : jsel;
;           if (lane < 8 && lane < nvalid - bt * 8) wbuf[(size_t)t * 128 + jsel] = val;
.Lgu_gloop:
	s_waitcnt lgkmcnt(0)
	ds_read_b32 v115, v101
	v_cmp_gt_u32_e64 s[54:55], s56, v102
	v_add_u32_e32 v101, 16, v101
	v_add_u32_e32 v102, 4, v102
	s_nop 0
	v_cndmask_b32_e64 v103, 0, v117, s[54:55]
	v_and_or_b32 v104, v103, s67, v96
	v_and_b32_e32 v107, 0x3ff, v103
	s_and_b64 s[54:55], s[54:55], s[8:9]
	global_load_dwordx4 v[144:147], v104, s[34:35]
	global_load_dwordx4 v[148:151], v104, s[34:35] offset:256
	global_load_dwordx4 v[152:155], v104, s[34:35] offset:512
	global_load_dwordx4 v[156:159], v104, s[34:35] offset:768
	s_waitcnt vmcnt(8)
	v_dot8_i32_i4 v108, v32, v0, 0
	v_dot8_i32_i4 v109, v32, v4, 0
	s_nop 1
	v_dot8c_i32_i4_e32 v108, v33, v1
	v_dot8c_i32_i4_e32 v109, v33, v5
	v_dot8c_i32_i4_e32 v108, v34, v2
	v_dot8c_i32_i4_e32 v109, v34, v6
	v_dot8c_i32_i4_e32 v108, v35, v3
	v_dot8c_i32_i4_e32 v109, v35, v7
	v_dot8c_i32_i4_e32 v108, v36, v8
	v_dot8c_i32_i4_e32 v109, v36, v12
	v_dot8c_i32_i4_e32 v108, v37, v9
	v_dot8c_i32_i4_e32 v109, v37, v13
	v_dot8c_i32_i4_e32 v108, v38, v10
	v_dot8c_i32_i4_e32 v109, v38, v14
	v_dot8c_i32_i4_e32 v108, v39, v11
	v_dot8c_i32_i4_e32 v109, v39, v15
	v_dot8c_i32_i4_e32 v108, v40, v16
	v_dot8c_i32_i4_e32 v109, v40, v20
	v_dot8c_i32_i4_e32 v108, v41, v17
	v_dot8c_i32_i4_e32 v109, v41, v21
	v_dot8c_i32_i4_e32 v108, v42, v18
	v_dot8c_i32_i4_e32 v109, v42, v22
	v_dot8c_i32_i4_e32 v108, v43, v19
	v_dot8c_i32_i4_e32 v109, v43, v23
	v_dot8c_i32_i4_e32 v108, v44, v24
	v_dot8c_i32_i4_e32 v109, v44, v28
	v_dot8c_i32_i4_e32 v108, v45, v25
	v_dot8c_i32_i4_e32 v109, v45, v29
	v_dot8c_i32_i4_e32 v108, v46, v26
	v_dot8c_i32_i4_e32 v109, v46, v30
	v_dot8c_i32_i4_e32 v108, v47, v27
	v_dot8c_i32_i4_e32 v109, v47, v31
	s_nop 2
	v_lshl_add_u32 v110, v108, 4, v109
	s_nop 1
	v_add_u32_dpp v110, v110, v110 quad_perm:[1,0,3,2] row_mask:0xf bank_mask:0xf
	s_nop 1
	v_add_u32_dpp v110, v110, v110 quad_perm:[2,3,0,1] row_mask:0xf bank_mask:0xf
	s_nop 1
	v_add_u32_dpp v110, v110, v110 row_half_mirror row_mask:0xf bank_mask:0xf
	s_nop 1
	v_add_u32_dpp v110, v110, v110 row_mirror row_mask:0xf bank_mask:0xf
	s_mov_b64 exec, s[50:51]
	global_store_dword v105, v110, s[48:49]
	s_mov_b64 exec, -1
	s_add_i32 s58, s58, 1
	s_cmp_ge_u32 s58, s57
	s_cbranch_scc1 .Lgu_tnext
	s_waitcnt lgkmcnt(0)
	ds_read_b32 v116, v101
	v_cmp_gt_u32_e64 s[50:51], s56, v102
	v_add_u32_e32 v101, 16, v101
	v_add_u32_e32 v102, 4, v102
	s_nop 0
	v_cndmask_b32_e64 v103, 0, v115, s[50:51]
	v_and_or_b32 v104, v103, s67, v96
	v_and_b32_e32 v105, 0x3ff, v103
	s_and_b64 s[50:51], s[50:51], s[8:9]
	global_load_dwordx4 v[32:35], v104, s[34:35]
	global_load_dwordx4 v[36:39], v104, s[34:35] offset:256
	global_load_dwordx4 v[40:43], v104, s[34:35] offset:512
	global_load_dwordx4 v[44:47], v104, s[34:35] offset:768
	s_waitcnt vmcnt(8)
	v_dot8_i32_i4 v108, v48, v0, 0
	v_dot8_i32_i4 v109, v48, v4, 0
	s_nop 1
	v_dot8c_i32_i4_e32 v108, v49, v1
	v_dot8c_i32_i4_e32 v109, v49, v5
	v_dot8c_i32_i4_e32 v108, v50, v2
	v_dot8c_i32_i4_e32 v109, v50, v6
	v_dot8c_i32_i4_e32 v108, v51, v3
	v_dot8c_i32_i4_e32 v109, v51, v7
	v_dot8c_i32_i4_e32 v108, v52, v8
	v_dot8c_i32_i4_e32 v109, v52, v12
	v_dot8c_i32_i4_e32 v108, v53, v9
	v_dot8c_i32_i4_e32 v109, v53, v13
	v_dot8c_i32_i4_e32 v108, v54, v10
	v_dot8c_i32_i4_e32 v109, v54, v14
	v_dot8c_i32_i4_e32 v108, v55, v11
	v_dot8c_i32_i4_e32 v109, v55, v15
	v_dot8c_i32_i4_e32 v108, v56, v16
	v_dot8c_i32_i4_e32 v109, v56, v20
	v_dot8c_i32_i4_e32 v108, v57, v17
	v_dot8c_i32_i4_e32 v109, v57, v21
	v_dot8c_i32_i4_e32 v108, v58, v18
	v_dot8c_i32_i4_e32 v109, v58, v22
	v_dot8c_i32_i4_e32 v108, v59, v19
	v_dot8c_i32_i4_e32 v109, v59, v23
	v_dot8c_i32_i4_e32 v108, v60, v24
	v_dot8c_i32_i4_e32 v109, v60, v28
	v_dot8c_i32_i4_e32 v108, v61, v25
	v_dot8c_i32_i4_e32 v109, v61, v29
	v_dot8c_i32_i4_e32 v108, v62, v26
	v_dot8c_i32_i4_e32 v109, v62, v30
	v_dot8c_i32_i4_e32 v108, v63, v27
	v_dot8c_i32_i4_e32 v109, v63, v31
	s_nop 2
	v_lshl_add_u32 v110, v108, 4, v109
	s_nop 1
	v_add_u32_dpp v110, v110, v110 quad_perm:[1,0,3,2] row_mask:0xf bank_mask:0xf
	s_nop 1
	v_add_u32_dpp v110, v110, v110 quad_perm:[2,3,0,1] row_mask:0xf bank_mask:0xf
	s_nop 1
	v_add_u32_dpp v110, v110, v110 row_half_mirror row_mask:0xf bank_mask:0xf
	s_nop 1
	v_add_u32_dpp v110, v110, v110 row_mirror row_mask:0xf bank_mask:0xf
	s_mov_b64 exec, s[52:53]
	global_store_dword v106, v110, s[48:49]
	s_mov_b64 exec, -1
	s_add_i32 s58, s58, 1
	s_cmp_ge_u32 s58, s57
	s_cbranch_scc1 .Lgu_tnext
	s_waitcnt lgkmcnt(0)
	ds_read_b32 v117, v101
	v_cmp_gt_u32_e64 s[52:53], s56, v102
	v_add_u32_e32 v101, 16, v101
	v_add_u32_e32 v102, 4, v102
	s_nop 0
	v_cndmask_b32_e64 v103, 0, v116, s[52:53]
	v_and_or_b32 v104, v103, s67, v96
	v_and_b32_e32 v106, 0x3ff, v103
	s_and_b64 s[52:53], s[52:53], s[8:9]
	global_load_dwordx4 v[48:51], v104, s[34:35]
	global_load_dwordx4 v[52:55], v104, s[34:35] offset:256
	global_load_dwordx4 v[56:59], v104, s[34:35] offset:512
	global_load_dwordx4 v[60:63], v104, s[34:35] offset:768
	s_waitcnt vmcnt(8)
	v_dot8_i32_i4 v108, v144, v0, 0
	v_dot8_i32_i4 v109, v144, v4, 0
	s_nop 1
	v_dot8c_i32_i4_e32 v108, v145, v1
	v_dot8c_i32_i4_e32 v109, v145, v5
	v_dot8c_i32_i4_e32 v108, v146, v2
	v_dot8c_i32_i4_e32 v109, v146, v6
	v_dot8c_i32_i4_e32 v108, v147, v3
	v_dot8c_i32_i4_e32 v109, v147, v7
	v_dot8c_i32_i4_e32 v108, v148, v8
	v_dot8c_i32_i4_e32 v109, v148, v12
	v_dot8c_i32_i4_e32 v108, v149, v9
	v_dot8c_i32_i4_e32 v109, v149, v13
	v_dot8c_i32_i4_e32 v108, v150, v10
	v_dot8c_i32_i4_e32 v109, v150, v14
	v_dot8c_i32_i4_e32 v108, v151, v11
	v_dot8c_i32_i4_e32 v109, v151, v15
	v_dot8c_i32_i4_e32 v108, v152, v16
	v_dot8c_i32_i4_e32 v109, v152, v20
	v_dot8c_i32_i4_e32 v108, v153, v17
	v_dot8c_i32_i4_e32 v109, v153, v21
	v_dot8c_i32_i4_e32 v108, v154, v18
	v_dot8c_i32_i4_e32 v109, v154, v22
	v_dot8c_i32_i4_e32 v108, v155, v19
	v_dot8c_i32_i4_e32 v109, v155, v23
	v_dot8c_i32_i4_e32 v108, v156, v24
	v_dot8c_i32_i4_e32 v109, v156, v28
	v_dot8c_i32_i4_e32 v108, v157, v25
	v_dot8c_i32_i4_e32 v109, v157, v29
	v_dot8c_i32_i4_e32 v108, v158, v26
	v_dot8c_i32_i4_e32 v109, v158, v30
	v_dot8c_i32_i4_e32 v108, v159, v27
	v_dot8c_i32_i4_e32 v109, v159, v31
	s_nop 2
	v_lshl_add_u32 v110, v108, 4, v109
	s_nop 1
	v_add_u32_dpp v110, v110, v110 quad_perm:[1,0,3,2] row_mask:0xf bank_mask:0xf
	s_nop 1
	v_add_u32_dpp v110, v110, v110 quad_perm:[2,3,0,1] row_mask:0xf bank_mask:0xf
	s_nop 1
	v_add_u32_dpp v110, v110, v110 row_half_mirror row_mask:0xf bank_mask:0xf
	s_nop 1
	v_add_u32_dpp v110, v110, v110 row_mirror row_mask:0xf bank_mask:0xf
	s_mov_b64 exec, s[54:55]
	global_store_dword v107, v110, s[48:49]
	s_mov_b64 exec, -1
	s_add_i32 s58, s58, 1
	s_cmp_lt_u32 s58, s57
	s_cbranch_scc1 .Lgu_gloop
